# SSD epilogue z-wait counts made exact for both wave halves (safe), on top of NSA fast paths + phase0 pipelining
# speedup vs baseline: 1.0025x; 1.0025x over previous
; #define MFMA32(a, b, c) __builtin_amdgcn_mfma_f32_32x32x16_bf16((a), (b), (c), 0, 0, 0)
; DI bf16x8 cat44(s16x4 a, s16x4 b) { return __builtin_shufflevector(a, b, 0, 1, 2, 3, 4, 5, 6, 7); }
; DI void ssd_pair_item(const Params& P, unsigned char* smem, int b, int hp) {
;     ...
;             for (int st = 0; st <= lt; ++st) {
;                 f32x16 S;
; #pragma unroll
;                 for (int i = 0; i < 16; ++i) S[i] = 0.f;
; #pragma unroll
;                 for (int ks = 0; ks < 8; ++ks) { const bf16x8 a = *(const bf16x8*)(smem + S2_BS + (32 * st + l32) * RS + (16 * ks + 8 * hh) * 2); S = MFMA32(a, CF2(ks), S); }
; #pragma unroll
;                 for (int ig = 0; ig < 4; ++ig) { const int s0 = 32 * st + 8 * ig + 4 * hh; const f32x4 cs = *(const f32x4*)(cum + s0), dv = *(const f32x4*)(dtv + s0);
; #pragma unroll
;                     for (int j = 0; j < 4; ++j) { const float dec = __expf(fminf(cl - cs[j], 0.f)) * dv[j]; S[4 * ig + j] = (s0 + j <= l) ? S[4 * ig + j] * dec : 0.f; } }
; #pragma unroll
;                 for (int s2 = 0; s2 < 2; ++s2) {
;                     const bf16x8 mf = pack8(S, s2);
;                     const unsigned char* xp = hb + S2_XT + (32 * ph + l32) * RS2 + (32 * st + 16 * s2 + 4 * hh) * 2;
;                     const bf16x8 a = cat44(*(const s16x4*)xp, *(const s16x4*)(xp + 16));
;                     acc = MFMA32(a, mf, acc);
;                 }
;             }
.LBB0_315:
	v_add_u32_e32 v207, 0, v176
	ds_read_b128 v[48:51], v207
	ds_read_b128 v[208:211], v207 offset:32
	v_add_u32_e32 v212, 0, v206
	v_cmp_le_i32_e32 vcc, v177, v174
	v_add_u32_e32 v175, -1, v175
	s_waitcnt lgkmcnt(1)
	v_mfma_f32_32x32x16_bf16 v[48:63], v[48:51], v[120:123], 0
	v_add_u32_e32 v206, 0x80, v206
	v_add_u32_e32 v176, 0x2200, v176
	s_waitcnt lgkmcnt(0)
	v_mfma_f32_32x32x16_bf16 v[48:63], v[208:211], v[124:127], v[48:63]
	ds_read_b128 v[208:211], v207 offset:64
	s_waitcnt lgkmcnt(0)
	v_mfma_f32_32x32x16_bf16 v[48:63], v[208:211], v[128:131], v[48:63]
	ds_read_b128 v[208:211], v207 offset:96
	s_waitcnt lgkmcnt(0)
	v_mfma_f32_32x32x16_bf16 v[48:63], v[208:211], v[132:135], v[48:63]
	ds_read_b128 v[208:211], v207 offset:128
	s_waitcnt lgkmcnt(0)
	v_mfma_f32_32x32x16_bf16 v[48:63], v[208:211], v[136:139], v[48:63]
	ds_read_b128 v[208:211], v207 offset:160
	s_waitcnt lgkmcnt(0)
	v_mfma_f32_32x32x16_bf16 v[48:63], v[208:211], v[140:143], v[48:63]
	ds_read_b128 v[208:211], v207 offset:192
	s_waitcnt lgkmcnt(0)
	v_mfma_f32_32x32x16_bf16 v[48:63], v[208:211], v[144:147], v[48:63]
	ds_read_b128 v[208:211], v207 offset:224
	v_add_u32_e32 v207, 0x13800, v212
	s_waitcnt lgkmcnt(0)
	v_mfma_f32_32x32x16_bf16 v[48:63], v[208:211], v[148:151], v[48:63]
	ds_read_b128 v[208:211], v207
	v_add_u32_e32 v207, 0x13a00, v212
	ds_read_b128 v[216:219], v207
	s_waitcnt lgkmcnt(1)
	v_sub_f32_e32 v207, v64, v208
	v_min_f32_e32 v207, 0, v207
	v_mul_f32_e32 v207, 0x3fb8aa3b, v207
	v_exp_f32_e32 v207, v207
	s_waitcnt lgkmcnt(0)
	v_mul_f32_e32 v207, v216, v207
	s_nop 1
	v_mul_f32_e32 v48, v48, v207
	v_cndmask_b32_e32 v208, 0, v48, vcc
	v_sub_f32_e32 v48, v64, v209
	v_min_f32_e32 v48, 0, v48
	v_mul_f32_e32 v48, 0x3fb8aa3b, v48
	v_exp_f32_e32 v48, v48
	v_cmp_lt_i32_e32 vcc, v177, v174
	v_add_u32_e32 v207, 8, v177
	v_mul_f32_e32 v48, v217, v48
	v_mul_f32_e32 v48, v49, v48
	v_cndmask_b32_e32 v209, 0, v48, vcc
	v_sub_f32_e32 v48, v64, v210
	v_sub_f32_e32 v49, v64, v211
	v_min_f32_e32 v48, 0, v48
	v_min_f32_e32 v49, 0, v49
	v_mul_f32_e32 v48, 0x3fb8aa3b, v48
	v_mul_f32_e32 v49, 0x3fb8aa3b, v49
	v_exp_f32_e32 v48, v48
	v_exp_f32_e32 v49, v49
	v_cmp_le_i32_e32 vcc, v207, v174
	v_or_b32_e32 v211, 2, v177
	v_or_b32_e32 v210, 3, v177
	v_pk_mul_f32 v[48:49], v[218:219], v[48:49]
	v_cvt_pk_bf16_f32 v208, v208, v209
	v_pk_mul_f32 v[48:49], v[50:51], v[48:49]
	v_add_u32_e32 v50, 0x13820, v212
	ds_read_b128 v[216:219], v50
	v_add_u32_e32 v50, 0x13a20, v212
	ds_read_b128 v[220:223], v50
	v_cvt_pk_bf16_f32 v48, v48, v49
	s_waitcnt lgkmcnt(1)
	v_sub_f32_e32 v50, v64, v216
	v_min_f32_e32 v50, 0, v50
	v_mul_f32_e32 v50, 0x3fb8aa3b, v50
	v_exp_f32_e32 v50, v50
	v_sub_f32_e32 v51, v64, v219
	v_min_f32_e32 v51, 0, v51
	v_mul_f32_e32 v51, 0x3fb8aa3b, v51
	s_waitcnt lgkmcnt(0)
	v_mul_f32_e32 v50, v220, v50
	v_mul_f32_e32 v50, v52, v50
	v_cndmask_b32_e32 v213, 0, v50, vcc
	v_sub_f32_e32 v50, v64, v217
	v_min_f32_e32 v50, 0, v50
	v_mul_f32_e32 v50, 0x3fb8aa3b, v50
	v_exp_f32_e32 v50, v50
	v_cmp_lt_i32_e32 vcc, v207, v174
	v_exp_f32_e32 v51, v51
	v_add_u32_e32 v52, 0x13840, v212
	v_mul_f32_e32 v50, v221, v50
	v_mul_f32_e32 v50, v53, v50
	v_cndmask_b32_e32 v214, 0, v50, vcc
	v_sub_f32_e32 v50, v64, v218
	v_min_f32_e32 v50, 0, v50
	v_mul_f32_e32 v50, 0x3fb8aa3b, v50
	v_exp_f32_e32 v50, v50
	v_add_u32_e32 v216, 0x13a40, v212
	ds_read_b128 v[216:219], v216
	v_or_b32_e32 v220, 3, v207
	v_pk_mul_f32 v[50:51], v[222:223], v[50:51]
	v_or_b32_e32 v221, 2, v207
	v_pk_mul_f32 v[50:51], v[54:55], v[50:51]
	ds_read_b128 v[52:55], v52
	v_add_u32_e32 v207, 16, v177
	v_cmp_le_i32_e32 vcc, v207, v174
	v_add_u32_e32 v223, 24, v177
	v_add_u32_e32 v177, 32, v177
	s_waitcnt lgkmcnt(0)
	v_sub_f32_e32 v52, v64, v52
	v_min_f32_e32 v52, 0, v52
	v_sub_f32_e32 v53, v64, v53
	v_mul_f32_e32 v52, 0x3fb8aa3b, v52
	v_min_f32_e32 v53, 0, v53
	v_exp_f32_e32 v52, v52
	v_mul_f32_e32 v53, 0x3fb8aa3b, v53
	v_exp_f32_e32 v53, v53
	v_mul_f32_e32 v52, v216, v52
	v_mul_f32_e32 v52, v56, v52
	v_mul_f32_e32 v53, v217, v53
	v_cndmask_b32_e32 v52, 0, v52, vcc
	v_cmp_lt_i32_e32 vcc, v207, v174
	v_mul_f32_e32 v53, v57, v53
	v_add_u32_e32 v56, 0x13860, v212
	v_cndmask_b32_e32 v222, 0, v53, vcc
	v_sub_f32_e32 v53, v64, v54
	v_min_f32_e32 v53, 0, v53
	v_mul_f32_e32 v53, 0x3fb8aa3b, v53
	v_exp_f32_e32 v54, v53
	v_sub_f32_e32 v53, v64, v55
	v_min_f32_e32 v53, 0, v53
	v_mul_f32_e32 v53, 0x3fb8aa3b, v53
	v_exp_f32_e32 v55, v53
	v_add_u32_e32 v212, 0x13a60, v212
	v_cmp_le_i32_e32 vcc, v223, v174
	v_or_b32_e32 v53, 3, v207
	v_pk_mul_f32 v[54:55], v[218:219], v[54:55]
	ds_read_b128 v[216:219], v212
	v_pk_mul_f32 v[54:55], v[58:59], v[54:55]
	ds_read_b128 v[56:59], v56
	v_or_b32_e32 v207, 2, v207
	v_cvt_pk_bf16_f32 v54, v54, v55
	v_cvt_pk_bf16_f32 v52, v52, v222
	s_waitcnt lgkmcnt(0)
	v_sub_f32_e32 v56, v64, v56
	v_min_f32_e32 v56, 0, v56
	v_mul_f32_e32 v56, 0x3fb8aa3b, v56
	v_exp_f32_e32 v56, v56
	s_nop 0
	v_mul_f32_e32 v56, v216, v56
	v_mul_f32_e32 v56, v60, v56
	v_cndmask_b32_e32 v60, 0, v56, vcc
	v_sub_f32_e32 v56, v64, v57
	v_min_f32_e32 v56, 0, v56
	v_mul_f32_e32 v56, 0x3fb8aa3b, v56
	v_exp_f32_e32 v56, v56
	v_cmp_lt_i32_e32 vcc, v223, v174
	v_sub_f32_e32 v57, v64, v59
	v_min_f32_e32 v57, 0, v57
	v_mul_f32_e32 v56, v217, v56
	v_mul_f32_e32 v56, v61, v56
	v_cndmask_b32_e32 v61, 0, v56, vcc
	v_sub_f32_e32 v56, v64, v58
	v_min_f32_e32 v56, 0, v56
	v_mul_f32_e32 v56, 0x3fb8aa3b, v56
	v_mul_f32_e32 v57, 0x3fb8aa3b, v57
	v_exp_f32_e32 v56, v56
	v_exp_f32_e32 v57, v57
	v_cmp_le_i32_e32 vcc, v211, v174
	v_or_b32_e32 v59, 2, v223
	v_or_b32_e32 v58, 3, v223
	v_cndmask_b32_e32 v49, 0, v48, vcc
	v_lshrrev_b32_e32 v48, 16, v48
	v_cmp_le_i32_e32 vcc, v210, v153
	v_pk_mul_f32 v[56:57], v[218:219], v[56:57]
	v_cvt_pk_bf16_f32 v210, v213, v214
	v_cndmask_b32_e32 v48, 0, v48, vcc
	v_perm_b32 v209, v48, v49, s94
	v_cvt_pk_bf16_f32 v48, v50, v51
	v_cmp_le_i32_e32 vcc, v221, v174
	v_pk_mul_f32 v[56:57], v[62:63], v[56:57]
	v_add_u32_e32 v62, 0, v205
	v_cndmask_b32_e32 v49, 0, v48, vcc
	v_lshrrev_b32_e32 v48, 16, v48
	v_cmp_le_i32_e32 vcc, v220, v153
	v_add_u32_e32 v205, 64, v205
	s_nop 0
	v_cndmask_b32_e32 v48, 0, v48, vcc
	v_perm_b32 v211, v48, v49, s94
	ds_read2_b64 v[216:219], v62 offset1:2
	ds_read2_b64 v[48:51], v62 offset0:4 offset1:6
	s_waitcnt lgkmcnt(1)
	v_mfma_f32_32x32x16_bf16 v[32:47], v[216:219], v[208:211], v[32:47]
	v_cmp_le_i32_e32 vcc, v207, v174
	s_nop 1
	v_cndmask_b32_e32 v55, 0, v54, vcc
	v_lshrrev_b32_e32 v54, 16, v54
	v_cmp_le_i32_e32 vcc, v53, v153
	s_nop 1
	v_cndmask_b32_e32 v53, 0, v54, vcc
	v_perm_b32 v53, v53, v55, s94
	v_cvt_pk_bf16_f32 v55, v56, v57
	v_cmp_le_i32_e32 vcc, v59, v174
	v_cvt_pk_bf16_f32 v54, v60, v61
	s_nop 0
	v_cndmask_b32_e32 v56, 0, v55, vcc
	v_lshrrev_b32_e32 v55, 16, v55
	v_cmp_le_i32_e32 vcc, v58, v153
	s_nop 1
	v_cndmask_b32_e32 v55, 0, v55, vcc
	v_perm_b32 v55, v55, v56, s94
	v_cmp_eq_u32_e32 vcc, 0, v175
	s_or_b64 s[2:3], vcc, s[2:3]
	s_waitcnt lgkmcnt(0)
	v_mfma_f32_32x32x16_bf16 v[32:47], v[48:51], v[52:55], v[32:47]
	s_andn2_b64 exec, exec, s[2:3]
	s_cbranch_execnz .LBB0_315
; DI int opaque_i(int v) { asm volatile("" : "+v"(v)); return v; }
; DI void ssd_pair_item(const Params& P, unsigned char* smem, int b, int hp) {
;     ...
;             const size_t tok = (size_t)b * TT + t0 + l; float ss = 0.f;
;             const int xo = opaque_i((32 * ph + 4 * hh) * RS2 + l * 2);
; #pragma unroll
;             for (int ig = 0; ig < 4; ++ig) { const int p0 = 32 * ph + 8 * ig + 4 * hh;
;                 const u32x2 zz = zr[ig];
	s_or_b64 exec, exec, s[2:3]
	v_add_u32_e32 v52, v204, v197
	v_mul_lo_u32 v50, v52, s92
	v_lshl_add_u32 v50, v174, 1, v50
	s_cmp_eq_u32 s33, 31
	s_cbranch_scc1 .Lssd_wA_0
	s_waitcnt vmcnt(13)
	s_branch .Lssd_wB_0

; DI float bf2f(bf16_t u) { return __uint_as_float(((unsigned)u) << 16); }
; DI unsigned pk2(float lo, float hi) { f32x2 v = {lo, hi}; bf16x2_t b = __builtin_convertvector(v, bf16x2_t); return __builtin_bit_cast(unsigned, b); }
; DI float lo16(unsigned u) { return __uint_as_float(u << 16); }
; DI float hi16(unsigned u) { return __uint_as_float(u & 0xffff0000u); }
; DI float siluf_(float x) { return x * __builtin_amdgcn_rcpf(1.f + __expf(-x)); }
; DI void ssd_pair_item(const Params& P, unsigned char* smem, int b, int hp) {
;     ...
;             for (int ig = 0; ig < 4; ++ig) { const int p0 = 32 * ph + 8 * ig + 4 * hh;
;                 const u32x2 zz = zr[ig];
;                 const float zf[4] = {lo16(zz.x), hi16(zz.x), lo16(zz.y), hi16(zz.y)}; float y[4];
; #pragma unroll
;                 for (int j = 0; j < 4; ++j) { const float xv = bf2f(*(const bf16_t*)(hb + S2_XT + xo + (8 * ig + j) * RS2)); y[j] = (acc[4 * ig + j] + Dsk * xv) * siluf_(zf[j]); ss += y[j] * y[j]; }
;                 u32x2 w; w.x = pk2(y[0], y[1]); w.y = pk2(y[2], y[3]);
;                 *(u32x2*)(P_yg + tok * 4096 + hd * 64 + p0) = w; }
.Lssd_wB_0:
	v_and_b32_e32 v51, 0xffff0000, v162
	v_add_u32_e32 v54, v192, v50
	v_lshlrev_b32_e32 v50, 16, v162
	v_mul_f32_e32 v53, 0xbfb8aa3b, v50
	v_exp_f32_e32 v53, v53
	v_mul_f32_e32 v55, 0xbfb8aa3b, v51
	v_exp_f32_e32 v55, v55
	s_add_u32 s0, s72, s82
	v_add_f32_e32 v53, 1.0, v53
	v_rcp_f32_e32 v58, v53
	v_add_f32_e32 v53, 1.0, v55
	v_rcp_f32_e32 v59, v53
	ds_read_u16 v53, v54 offset:53248
	ds_read_u16 v55, v54 offset:53392
	ds_read_u16 v62, v54 offset:53536
	ds_read_u16 v63, v54 offset:53680
	ds_read_u16 v64, v54 offset:54400
	ds_read_u16 v120, v54 offset:54544
	ds_read_u16 v121, v54 offset:54688
	ds_read_u16 v122, v54 offset:54832
	s_waitcnt lgkmcnt(6)
	v_lshlrev_b32_e32 v61, 16, v55
	v_lshlrev_b32_e32 v60, 16, v53
	v_pk_fma_f32 v[32:33], v[156:157], v[60:61], v[32:33]
	v_pk_mul_f32 v[50:51], v[58:59], v[50:51]
	v_lshlrev_b32_e32 v58, 16, v163
	v_pk_mul_f32 v[32:33], v[50:51], v[32:33]
	v_and_b32_e32 v59, 0xffff0000, v163
	v_mul_f32_e32 v50, 0xbfb8aa3b, v58
	v_exp_f32_e32 v53, v50
	v_mul_f32_e32 v50, 0xbfb8aa3b, v59
	v_exp_f32_e32 v55, v50
	v_ashrrev_i32_e32 v175, 31, v174
	v_add_f32_e32 v53, 1.0, v53
	v_rcp_f32_e32 v60, v53
	v_add_f32_e32 v53, 1.0, v55
	v_rcp_f32_e32 v61, v53
	s_addc_u32 s1, s73, 0
	v_lshl_add_u64 v[48:49], s[0:1], 0, v[174:175]
	v_lshlrev_b64 v[56:57], 13, v[48:49]
	v_pk_mul_f32 v[50:51], v[32:33], v[32:33]
	v_pk_mul_f32 v[58:59], v[60:61], v[58:59]
	v_cvt_pk_bf16_f32 v60, v32, v33
	v_lshl_add_u64 v[32:33], v[160:161], 0, v[56:57]
	v_ashrrev_i32_e32 v53, 31, v52
	v_lshl_add_u64 v[32:33], v[52:53], 1, v[32:33]
	s_cmp_eq_u32 s33, 31
	s_cbranch_scc1 .Lssd_wA_1
	s_waitcnt vmcnt(12)
	s_branch .Lssd_wB_1

; DI float bf2f(bf16_t u) { return __uint_as_float(((unsigned)u) << 16); }
; DI unsigned pk2(float lo, float hi) { f32x2 v = {lo, hi}; bf16x2_t b = __builtin_convertvector(v, bf16x2_t); return __builtin_bit_cast(unsigned, b); }
; DI float lo16(unsigned u) { return __uint_as_float(u << 16); }
; DI float hi16(unsigned u) { return __uint_as_float(u & 0xffff0000u); }
; DI float siluf_(float x) { return x * __builtin_amdgcn_rcpf(1.f + __expf(-x)); }
; DI void ssd_pair_item(const Params& P, unsigned char* smem, int b, int hp) {
;     ...
;             for (int ig = 0; ig < 4; ++ig) { const int p0 = 32 * ph + 8 * ig + 4 * hh;
;                 const u32x2 zz = zr[ig];
;                 const float zf[4] = {lo16(zz.x), hi16(zz.x), lo16(zz.y), hi16(zz.y)}; float y[4];
; #pragma unroll
;                 for (int j = 0; j < 4; ++j) { const float xv = bf2f(*(const bf16_t*)(hb + S2_XT + xo + (8 * ig + j) * RS2)); y[j] = (acc[4 * ig + j] + Dsk * xv) * siluf_(zf[j]); ss += y[j] * y[j]; }
;                 u32x2 w; w.x = pk2(y[0], y[1]); w.y = pk2(y[2], y[3]);
;                 *(u32x2*)(P_yg + tok * 4096 + hd * 64 + p0) = w; }
.Lssd_wB_1:
	v_lshlrev_b32_e32 v52, 16, v166
	v_and_b32_e32 v53, 0xffff0000, v166
	v_mul_f32_e32 v55, 0xbfb8aa3b, v52
	v_exp_f32_e32 v55, v55
	v_mul_f32_e32 v56, 0xbfb8aa3b, v53
	v_exp_f32_e32 v57, v56
	s_waitcnt lgkmcnt(4)
	v_lshlrev_b32_e32 v63, 16, v63
	v_add_f32_e32 v55, 1.0, v55
	v_rcp_f32_e32 v56, v55
	v_add_f32_e32 v55, 1.0, v57
	v_lshlrev_b32_e32 v62, 16, v62
	v_rcp_f32_e32 v57, v55
	v_pk_fma_f32 v[34:35], v[156:157], v[62:63], v[34:35]
	v_add_f32_e32 v50, v50, v51
	v_pk_mul_f32 v[58:59], v[58:59], v[34:35]
	v_pk_mul_f32 v[52:53], v[56:57], v[52:53]
	v_pk_mul_f32 v[34:35], v[58:59], v[58:59]
	v_cvt_pk_bf16_f32 v61, v58, v59
	s_waitcnt lgkmcnt(2)
	v_lshlrev_b32_e32 v59, 16, v120
	v_lshlrev_b32_e32 v58, 16, v64
	v_pk_fma_f32 v[36:37], v[156:157], v[58:59], v[36:37]
	v_lshlrev_b32_e32 v56, 16, v167
	v_pk_mul_f32 v[52:53], v[52:53], v[36:37]
	v_and_b32_e32 v57, 0xffff0000, v167
	v_mul_f32_e32 v36, 0xbfb8aa3b, v56
	v_exp_f32_e32 v55, v36
	v_mul_f32_e32 v36, 0xbfb8aa3b, v57
	v_exp_f32_e32 v59, v36
	global_store_dwordx2 v[32:33], v[60:61], off
	v_add_f32_e32 v55, 1.0, v55
	v_rcp_f32_e32 v58, v55
	v_add_f32_e32 v55, 1.0, v59
	v_rcp_f32_e32 v59, v55
	s_waitcnt lgkmcnt(0)
	v_lshlrev_b32_e32 v61, 16, v122
	v_lshlrev_b32_e32 v60, 16, v121
	v_pk_fma_f32 v[38:39], v[156:157], v[60:61], v[38:39]
	v_pk_mul_f32 v[56:57], v[58:59], v[56:57]
	v_pk_mul_f32 v[36:37], v[52:53], v[52:53]
	v_pk_mul_f32 v[56:57], v[56:57], v[38:39]
	v_cvt_pk_bf16_f32 v52, v52, v53
	v_pk_mul_f32 v[38:39], v[56:57], v[56:57]
	v_cvt_pk_bf16_f32 v53, v56, v57
	s_cmp_eq_u32 s33, 31
	s_cbranch_scc1 .Lssd_wA_2
	s_waitcnt vmcnt(12)
	s_branch .Lssd_wB_2

; #define P_part   WSP(float, WS_PART)
; DI float bf2f(bf16_t u) { return __uint_as_float(((unsigned)u) << 16); }
; DI unsigned pk2(float lo, float hi) { f32x2 v = {lo, hi}; bf16x2_t b = __builtin_convertvector(v, bf16x2_t); return __builtin_bit_cast(unsigned, b); }
; DI float lo16(unsigned u) { return __uint_as_float(u << 16); }
; DI float hi16(unsigned u) { return __uint_as_float(u & 0xffff0000u); }
; DI float siluf_(float x) { return x * __builtin_amdgcn_rcpf(1.f + __expf(-x)); }
; DI void ssd_pair_item(const Params& P, unsigned char* smem, int b, int hp) {
;     ...
;             for (int ig = 0; ig < 4; ++ig) { const int p0 = 32 * ph + 8 * ig + 4 * hh;
;                 const u32x2 zz = zr[ig];
;                 const float zf[4] = {lo16(zz.x), hi16(zz.x), lo16(zz.y), hi16(zz.y)}; float y[4];
; #pragma unroll
;                 for (int j = 0; j < 4; ++j) { const float xv = bf2f(*(const bf16_t*)(hb + S2_XT + xo + (8 * ig + j) * RS2)); y[j] = (acc[4 * ig + j] + Dsk * xv) * siluf_(zf[j]); ss += y[j] * y[j]; }
;                 u32x2 w; w.x = pk2(y[0], y[1]); w.y = pk2(y[2], y[3]);
;                 *(u32x2*)(P_yg + tok * 4096 + hd * 64 + p0) = w; }
;             ss += __shfl_xor(ss, 32);
;             if (hh == 0) P_part[tok * 64 + hd * 2 + ph] = ss;
.Lssd_wB_2:
	v_lshlrev_b32_e32 v56, 16, v168
	v_and_b32_e32 v57, 0xffff0000, v168
	v_mul_f32_e32 v55, 0xbfb8aa3b, v56
	v_mul_f32_e32 v58, 0xbfb8aa3b, v57
	v_exp_f32_e32 v55, v55
	v_exp_f32_e32 v58, v58
	global_store_dwordx2 v[32:33], v[52:53], off offset:16
	v_add_f32_e32 v34, v50, v34
	v_add_f32_e32 v52, 1.0, v55
	v_add_f32_e32 v53, 1.0, v58
	v_rcp_f32_e32 v52, v52
	v_rcp_f32_e32 v53, v53
	ds_read_u16 v58, v54 offset:55552
	ds_read_u16 v55, v54 offset:55696
	ds_read_u16 v60, v54 offset:55840
	ds_read_u16 v59, v54 offset:55984
	ds_read_u16 v61, v54 offset:56704
	ds_read_u16 v62, v54 offset:56848
	ds_read_u16 v63, v54 offset:56992
	ds_read_u16 v64, v54 offset:57136
	s_waitcnt lgkmcnt(6)
	v_lshlrev_b32_e32 v55, 16, v55
	v_lshlrev_b32_e32 v54, 16, v58
	v_pk_fma_f32 v[40:41], v[156:157], v[54:55], v[40:41]
	v_pk_mul_f32 v[52:53], v[52:53], v[56:57]
	s_waitcnt lgkmcnt(4)
	v_lshlrev_b32_e32 v59, 16, v59
	v_pk_mul_f32 v[40:41], v[52:53], v[40:41]
	v_lshlrev_b32_e32 v52, 16, v169
	v_and_b32_e32 v53, 0xffff0000, v169
	v_mul_f32_e32 v54, 0xbfb8aa3b, v52
	v_exp_f32_e32 v56, v54
	v_mul_f32_e32 v54, 0xbfb8aa3b, v53
	v_exp_f32_e32 v57, v54
	v_lshlrev_b32_e32 v58, 16, v60
	v_add_f32_e32 v56, 1.0, v56
	v_rcp_f32_e32 v56, v56
	v_add_f32_e32 v57, 1.0, v57
	v_rcp_f32_e32 v57, v57
	v_pk_fma_f32 v[42:43], v[156:157], v[58:59], v[42:43]
	v_pk_mul_f32 v[54:55], v[40:41], v[40:41]
	v_cvt_pk_bf16_f32 v40, v40, v41
	v_pk_mul_f32 v[52:53], v[56:57], v[52:53]
	v_add_f32_e32 v34, v34, v35
	v_pk_mul_f32 v[42:43], v[52:53], v[42:43]
	v_add_f32_e32 v34, v34, v36
	v_pk_mul_f32 v[52:53], v[42:43], v[42:43]
	v_cvt_pk_bf16_f32 v41, v42, v43
	s_cmp_eq_u32 s33, 31
	s_cbranch_scc1 .Lssd_wA_3
	s_waitcnt vmcnt(12)
	s_branch .Lssd_wB_3
